# prologue outputs (XN rows, transposed w_in tiles, AB rows) stored write-through (sc1): no dirty-L2 flush inside the first grid barrier
# speedup vs baseline: 1.4053x; 1.0097x over previous
.LBB0_32:
	s_mul_hi_i32 s6, s9, 0x92492493
	s_add_i32 s6, s6, s9
	s_lshr_b32 s7, s6, 31
	s_ashr_i32 s6, s6, 6
	s_add_i32 s7, s6, s7
	s_mul_i32 s16, s7, 0xffffff90
	s_lshl_b32 s6, s7, 6
	s_add_i32 s16, s9, s16
	s_cmp_gt_i32 s16, 63
	s_mul_i32 s17, s7, 0xe00
	s_cselect_b32 s16, 8, 0
	s_sub_i32 s16, s16, s17
	s_add_i32 s16, s4, s16
	v_or_b32_e32 v15, s6, v4
	s_ashr_i32 s17, s16, 31
	v_or_b32_e32 v30, 12, v15
	v_or_b32_e32 v32, 14, v15
	v_or_b32_e32 v34, 16, v15
	v_or_b32_e32 v36, 18, v15
	v_or_b32_e32 v38, 20, v15
	v_or_b32_e32 v40, 22, v15
	v_or_b32_e32 v42, 24, v15
	v_or_b32_e32 v44, 26, v15
	v_or_b32_e32 v46, 28, v15
	v_or_b32_e32 v48, 30, v15
	v_or_b32_e32 v50, 32, v15
	v_or_b32_e32 v52, 34, v15
	v_or_b32_e32 v54, 36, v15
	v_lshl_add_u64 v[16:17], s[16:17], 2, v[0:1]
	v_or_b32_e32 v20, 2, v15
	v_or_b32_e32 v22, 4, v15
	v_or_b32_e32 v24, 6, v15
	v_or_b32_e32 v26, 8, v15
	v_or_b32_e32 v28, 10, v15
	v_or_b32_e32 v56, 38, v15
	v_or_b32_e32 v58, 40, v15
	v_or_b32_e32 v60, 42, v15
	v_or_b32_e32 v62, 44, v15
	v_or_b32_e32 v64, 46, v15
	v_or_b32_e32 v66, 48, v15
	v_or_b32_e32 v68, 50, v15
	v_or_b32_e32 v70, 52, v15
	v_or_b32_e32 v72, 54, v15
	v_or_b32_e32 v74, 56, v15
	v_or_b32_e32 v76, 58, v15
	v_or_b32_e32 v78, 60, v15
	v_or_b32_e32 v80, 62, v15
	v_mad_i64_i32 v[18:19], s[16:17], v15, s8, v[16:17]
	v_mad_i64_i32 v[30:31], s[16:17], v30, s8, v[16:17]
	v_mad_i64_i32 v[32:33], s[16:17], v32, s8, v[16:17]
	v_mad_i64_i32 v[34:35], s[16:17], v34, s8, v[16:17]
	v_mad_i64_i32 v[36:37], s[16:17], v36, s8, v[16:17]
	v_mad_i64_i32 v[38:39], s[16:17], v38, s8, v[16:17]
	v_mad_i64_i32 v[40:41], s[16:17], v40, s8, v[16:17]
	v_mad_i64_i32 v[42:43], s[16:17], v42, s8, v[16:17]
	v_mad_i64_i32 v[44:45], s[16:17], v44, s8, v[16:17]
	v_mad_i64_i32 v[46:47], s[16:17], v46, s8, v[16:17]
	v_mad_i64_i32 v[48:49], s[16:17], v48, s8, v[16:17]
	v_mad_i64_i32 v[50:51], s[16:17], v50, s8, v[16:17]
	v_mad_i64_i32 v[52:53], s[16:17], v52, s8, v[16:17]
	v_mad_i64_i32 v[54:55], s[16:17], v54, s8, v[16:17]
	v_mad_i64_i32 v[20:21], s[16:17], v20, s8, v[16:17]
	v_mad_i64_i32 v[22:23], s[16:17], v22, s8, v[16:17]
	v_mad_i64_i32 v[24:25], s[16:17], v24, s8, v[16:17]
	v_mad_i64_i32 v[26:27], s[16:17], v26, s8, v[16:17]
	v_mad_i64_i32 v[28:29], s[16:17], v28, s8, v[16:17]
	v_mad_i64_i32 v[56:57], s[16:17], v56, s8, v[16:17]
	v_mad_i64_i32 v[58:59], s[16:17], v58, s8, v[16:17]
	v_mad_i64_i32 v[60:61], s[16:17], v60, s8, v[16:17]
	v_mad_i64_i32 v[62:63], s[16:17], v62, s8, v[16:17]
	v_mad_i64_i32 v[64:65], s[16:17], v64, s8, v[16:17]
	v_mad_i64_i32 v[66:67], s[16:17], v66, s8, v[16:17]
	v_mad_i64_i32 v[68:69], s[16:17], v68, s8, v[16:17]
	v_mad_i64_i32 v[70:71], s[16:17], v70, s8, v[16:17]
	v_mad_i64_i32 v[72:73], s[16:17], v72, s8, v[16:17]
	v_mad_i64_i32 v[74:75], s[16:17], v74, s8, v[16:17]
	v_mad_i64_i32 v[76:77], s[16:17], v76, s8, v[16:17]
	v_mad_i64_i32 v[78:79], s[16:17], v78, s8, v[16:17]
	v_mad_i64_i32 v[16:17], s[16:17], v80, s8, v[16:17]
	global_load_dword v15, v[18:19], off nt
	global_load_dword v80, v[20:21], off nt
	global_load_dword v81, v[22:23], off nt
	global_load_dword v82, v[24:25], off nt
	global_load_dword v83, v[26:27], off nt
	global_load_dword v84, v[28:29], off nt
	s_nop 0
	global_load_dword v30, v[30:31], off nt
	s_nop 0
	global_load_dword v31, v[32:33], off nt
	s_nop 0
	global_load_dword v32, v[34:35], off nt
	global_load_dword v33, v[36:37], off nt
	s_nop 0
	global_load_dword v34, v[38:39], off nt
	global_load_dword v35, v[40:41], off nt
	global_load_dword v36, v[42:43], off nt
	global_load_dword v37, v[44:45], off nt
	s_nop 0
	global_load_dword v38, v[46:47], off nt
	global_load_dword v39, v[48:49], off nt
	global_load_dword v40, v[50:51], off nt
	global_load_dword v41, v[52:53], off nt
	global_load_dword v42, v[54:55], off nt
	global_load_dword v43, v[56:57], off nt
	global_load_dword v44, v[58:59], off nt
	global_load_dword v45, v[60:61], off nt
	global_load_dword v46, v[62:63], off nt
	global_load_dword v47, v[64:65], off nt
	global_load_dword v48, v[66:67], off nt
	global_load_dword v49, v[68:69], off nt
	global_load_dword v50, v[70:71], off nt
	global_load_dword v51, v[72:73], off nt
	global_load_dword v52, v[74:75], off nt
	global_load_dword v53, v[76:77], off nt
	global_load_dword v54, v[78:79], off nt
	global_load_dword v55, v[16:17], off nt
	s_mul_i32 s16, s7, 0xfffff200
	s_add_i32 s16, s16, s4
	v_add_u32_e32 v22, s16, v5
	v_add_u32_e32 v16, 8, v22
	s_ashr_i32 s7, s6, 31
	v_add_u32_e32 v18, 16, v22
	v_ashrrev_i32_e32 v17, 31, v16
	s_waitcnt vmcnt(30)
	ds_write2_b32 v7, v15, v80 offset1:66
	s_waitcnt vmcnt(28)
	ds_write2_b32 v7, v81, v82 offset0:132 offset1:198
	s_waitcnt vmcnt(26)
	ds_write2_b32 v8, v83, v84 offset0:8 offset1:74
	s_waitcnt vmcnt(24)
	ds_write2_b32 v8, v30, v31 offset0:140 offset1:206
	s_waitcnt vmcnt(22)
	ds_write2_b32 v9, v32, v33 offset0:16 offset1:82
	s_waitcnt vmcnt(20)
	ds_write2_b32 v9, v34, v35 offset0:148 offset1:214
	s_waitcnt vmcnt(18)
	ds_write2_b32 v10, v36, v37 offset0:24 offset1:90
	s_waitcnt vmcnt(16)
	ds_write2_b32 v10, v38, v39 offset0:156 offset1:222
	s_waitcnt vmcnt(14)
	ds_write2_b32 v11, v40, v41 offset0:32 offset1:98
	s_waitcnt vmcnt(12)
	ds_write2_b32 v11, v42, v43 offset0:164 offset1:230
	s_waitcnt vmcnt(10)
	ds_write2_b32 v12, v44, v45 offset0:40 offset1:106
	s_waitcnt vmcnt(8)
	ds_write2_b32 v12, v46, v47 offset0:172 offset1:238
	s_waitcnt vmcnt(6)
	ds_write2_b32 v13, v48, v49 offset0:48 offset1:114
	s_waitcnt vmcnt(4)
	ds_write2_b32 v13, v50, v51 offset0:180 offset1:246
	s_waitcnt vmcnt(2)
	ds_write2_b32 v14, v52, v53 offset0:56 offset1:122
	s_waitcnt vmcnt(0)
	ds_write2_b32 v14, v54, v55 offset0:188 offset1:254
	v_lshl_add_u64 v[20:21], s[6:7], 1, v[2:3]
	v_ashrrev_i32_e32 v19, 31, v18
	v_lshlrev_b64 v[16:17], 11, v[16:17]
	s_waitcnt lgkmcnt(0)
	v_lshlrev_b64 v[18:19], 11, v[18:19]
	v_lshl_add_u64 v[26:27], v[20:21], 0, v[16:17]
	ds_read2_b32 v[16:17], v6 offset1:33
	v_ashrrev_i32_e32 v23, 31, v22
	v_lshl_add_u64 v[28:29], v[20:21], 0, v[18:19]
	s_waitcnt lgkmcnt(0)
	v_cvt_pk_bf16_f32 v16, v16, v17
	ds_read2_b32 v[18:19], v6 offset0:66 offset1:99
	v_lshlrev_b64 v[24:25], 11, v[22:23]
	s_waitcnt lgkmcnt(0)
	v_cvt_pk_bf16_f32 v17, v18, v19
	ds_read2_b32 v[18:19], v6 offset0:132 offset1:165
	v_lshl_add_u64 v[24:25], v[20:21], 0, v[24:25]
	s_waitcnt lgkmcnt(0)
	v_cvt_pk_bf16_f32 v18, v18, v19
	ds_read2_b32 v[30:31], v6 offset0:198 offset1:231
	s_waitcnt lgkmcnt(0)
	v_cvt_pk_bf16_f32 v19, v30, v31
	ds_read2_b32 v[30:31], v6 offset0:8 offset1:41
	global_store_dwordx4 v[24:25], v[16:19], off sc1
	v_add_u32_e32 v22, 24, v22
	v_ashrrev_i32_e32 v23, 31, v22
	s_waitcnt lgkmcnt(0)
	v_cvt_pk_bf16_f32 v16, v30, v31
	ds_read2_b32 v[18:19], v6 offset0:74 offset1:107
	s_waitcnt lgkmcnt(0)
	v_cvt_pk_bf16_f32 v17, v18, v19
	ds_read2_b32 v[18:19], v6 offset0:140 offset1:173
	s_waitcnt lgkmcnt(0)
	v_cvt_pk_bf16_f32 v18, v18, v19
	ds_read2_b32 v[24:25], v6 offset0:206 offset1:239
	s_waitcnt lgkmcnt(0)
	v_cvt_pk_bf16_f32 v19, v24, v25
	ds_read2_b32 v[24:25], v6 offset0:16 offset1:49
	global_store_dwordx4 v[26:27], v[16:19], off sc1
	v_lshlrev_b64 v[22:23], 11, v[22:23]
	v_lshl_add_u64 v[20:21], v[20:21], 0, v[22:23]
	s_waitcnt lgkmcnt(0)
	v_cvt_pk_bf16_f32 v16, v24, v25
	ds_read2_b32 v[18:19], v6 offset0:82 offset1:115
	s_waitcnt lgkmcnt(0)
	v_cvt_pk_bf16_f32 v17, v18, v19
	ds_read2_b32 v[18:19], v6 offset0:148 offset1:181
	s_waitcnt lgkmcnt(0)
	v_cvt_pk_bf16_f32 v18, v18, v19
	ds_read2_b32 v[24:25], v6 offset0:214 offset1:247
	s_waitcnt lgkmcnt(0)
	v_cvt_pk_bf16_f32 v19, v24, v25
	ds_read2_b32 v[24:25], v6 offset0:24 offset1:57
	global_store_dwordx4 v[28:29], v[16:19], off sc1
	s_add_i32 s9, s9, s3
	s_add_i32 s4, s4, s5
	s_waitcnt lgkmcnt(0)
	v_cvt_pk_bf16_f32 v16, v24, v25
	ds_read2_b32 v[18:19], v6 offset0:90 offset1:123
	s_waitcnt lgkmcnt(0)
	v_cvt_pk_bf16_f32 v17, v18, v19
	ds_read2_b32 v[18:19], v6 offset0:156 offset1:189
	s_waitcnt lgkmcnt(0)
	v_cvt_pk_bf16_f32 v18, v18, v19
	ds_read2_b32 v[24:25], v6 offset0:222 offset1:255
	s_waitcnt lgkmcnt(0)
	v_cvt_pk_bf16_f32 v19, v24, v25
	global_store_dwordx4 v[20:21], v[16:19], off sc1
	s_waitcnt lgkmcnt(0)
	s_cmpk_gt_i32 s9, 0x6ff
	s_cbranch_scc0 .LBB0_32

.LBB0_35:
	s_or_b64 exec, exec, s[16:17]
	v_lshlrev_b64 v[20:21], 11, v[40:41]
	v_mul_f32_e32 v12, v12, v32
	v_mul_f32_e32 v13, v13, v32
	v_mul_f32_e32 v14, v14, v32
	v_mul_f32_e32 v15, v15, v32
	v_lshl_add_u64 v[20:21], v[38:39], 0, v[20:21]
	v_mul_f32_e32 v8, v8, v32
	v_mul_f32_e32 v9, v9, v32
	v_mul_f32_e32 v10, v10, v32
	v_mul_f32_e32 v11, v11, v32
	v_mul_f32_e32 v4, v4, v32
	v_mul_f32_e32 v5, v5, v32
	v_mul_f32_e32 v6, v6, v32
	v_mul_f32_e32 v7, v7, v32
	v_mul_f32_e32 v0, v0, v32
	v_mul_f32_e32 v1, v1, v32
	v_mul_f32_e32 v2, v2, v32
	v_mul_f32_e32 v3, v3, v32
	v_mul_f32_e32 v12, v12, v76
	v_mul_f32_e32 v13, v13, v77
	v_mul_f32_e32 v14, v14, v78
	v_mul_f32_e32 v15, v15, v79
	v_cvt_pk_bf16_f32 v12, v12, v13
	v_cvt_pk_bf16_f32 v13, v14, v15
	global_store_dwordx2 v[20:21], v[12:13], off sc1
	v_mul_f32_e32 v8, v8, v80
	v_mul_f32_e32 v9, v9, v81
	v_mul_f32_e32 v10, v10, v82
	v_mul_f32_e32 v11, v11, v83
	v_cvt_pk_bf16_f32 v8, v8, v9
	v_cvt_pk_bf16_f32 v9, v10, v11
	global_store_dwordx2 v[20:21], v[8:9], off offset:512 sc1
	v_mul_f32_e32 v4, v4, v84
	v_mul_f32_e32 v5, v5, v85
	v_mul_f32_e32 v6, v6, v86
	v_mul_f32_e32 v7, v7, v87
	v_cvt_pk_bf16_f32 v4, v4, v5
	v_cvt_pk_bf16_f32 v5, v6, v7
	global_store_dwordx2 v[20:21], v[4:5], off offset:1024 sc1
	v_mul_f32_e32 v0, v0, v88
	v_mul_f32_e32 v1, v1, v89
	v_mul_f32_e32 v2, v2, v90
	v_mul_f32_e32 v3, v3, v91
	v_cvt_pk_bf16_f32 v0, v0, v1
	v_cvt_pk_bf16_f32 v1, v2, v3
	global_store_dwordx2 v[20:21], v[0:1], off offset:1536 sc1

.LBB0_37:
	s_ashr_i32 s47, s46, 31
	ds_read_b128 v[40:43], v57
	ds_read_b128 v[44:47], v57 offset:1024
	ds_read_b128 v[48:51], v57 offset:2048
	ds_read_b128 v[52:55], v57 offset:3072
	ds_read_b128 v[58:61], v57 offset:4096
	ds_read_b128 v[62:65], v57 offset:5120
	s_add_i32 s14, s46, s3
	s_waitcnt vmcnt(12)
	v_mov_b64_e32 v[28:29], v[92:93]
	v_mov_b64_e32 v[30:31], v[94:95]
	v_mov_b64_e32 v[24:25], v[96:97]
	v_mov_b64_e32 v[26:27], v[98:99]
	v_mov_b64_e32 v[20:21], v[100:101]
	v_mov_b64_e32 v[22:23], v[102:103]
	v_mov_b64_e32 v[16:17], v[104:105]
	v_mov_b64_e32 v[18:19], v[106:107]
	v_mov_b64_e32 v[12:13], v[108:109]
	v_mov_b64_e32 v[14:15], v[110:111]
	v_mov_b64_e32 v[8:9], v[112:113]
	v_mov_b64_e32 v[10:11], v[114:115]
	v_mov_b64_e32 v[4:5], v[116:117]
	v_mov_b64_e32 v[6:7], v[118:119]
	v_mov_b64_e32 v[0:1], v[120:121]
	v_mov_b64_e32 v[2:3], v[122:123]
	s_add_i32 s8, s14, s3
	s_min_i32 s8, s8, 0x3fff
	s_ashr_i32 s9, s8, 31
	s_lshl_b64 s[8:9], s[8:9], 12
	v_lshl_add_u64 v[124:125], v[36:37], 0, s[8:9]
	global_load_dwordx4 v[92:95], v[124:125], off nt
	global_load_dwordx4 v[96:99], v[124:125], off offset:1024 nt
	global_load_dwordx4 v[100:103], v[124:125], off offset:2048 nt
	global_load_dwordx4 v[104:107], v[124:125], off offset:3072 nt
	s_add_i32 s8, s14, s3
	s_add_i32 s8, s8, s3
	s_min_i32 s8, s8, 0x3fff
	s_ashr_i32 s9, s8, 31
	s_lshl_b64 s[8:9], s[8:9], 12
	v_lshl_add_u64 v[124:125], v[36:37], 0, s[8:9]
	global_load_dwordx4 v[108:111], v[124:125], off nt
	global_load_dwordx4 v[112:115], v[124:125], off offset:1024 nt
	global_load_dwordx4 v[116:119], v[124:125], off offset:2048 nt
	global_load_dwordx4 v[120:123], v[124:125], off offset:3072 nt
	v_mul_f32_e32 v32, v29, v29
	v_mul_f32_e32 v66, v31, v31
	v_mul_f32_e32 v67, v25, v25
	v_mul_f32_e32 v68, v27, v27
	v_mul_f32_e32 v69, v21, v21
	v_mul_f32_e32 v70, v23, v23
	s_waitcnt lgkmcnt(5)
	v_mul_f32_e32 v41, v29, v41
	v_fmac_f32_e32 v32, v28, v28
	v_fmac_f32_e32 v66, v30, v30
	v_fmac_f32_e32 v67, v24, v24
	v_fmac_f32_e32 v68, v26, v26
	v_mul_f32_e32 v71, v17, v17
	v_mul_f32_e32 v72, v19, v19
	v_mul_f32_e32 v43, v31, v43
	v_fmac_f32_e32 v69, v20, v20
	v_fmac_f32_e32 v70, v22, v22
	v_fmac_f32_e32 v41, v28, v40
	v_add_f32_e32 v32, v32, v66
	v_add_f32_e32 v40, v67, v68
	s_waitcnt lgkmcnt(4)
	v_mul_f32_e32 v45, v25, v45
	v_fmac_f32_e32 v71, v16, v16
	v_fmac_f32_e32 v72, v18, v18
	v_fmac_f32_e32 v43, v30, v42
	v_add_f32_e32 v42, v69, v70
	v_add_f32_e32 v32, v32, v40
	v_fmac_f32_e32 v45, v24, v44
	v_add_f32_e32 v44, v71, v72
	v_add_f32_e32 v32, v32, v42
	v_add_f32_e32 v32, v32, v44
	v_mul_f32_e32 v47, v27, v47
	s_waitcnt lgkmcnt(3)
	v_mul_f32_e32 v49, v21, v49
	v_add_f32_dpp v32, v32, v32 quad_perm:[1,0,3,2] row_mask:0xf bank_mask:0xf bound_ctrl:1
	v_mul_f32_e32 v51, v23, v51
	v_fmac_f32_e32 v47, v26, v46
	v_add_f32_dpp v32, v32, v32 quad_perm:[2,3,0,1] row_mask:0xf bank_mask:0xf bound_ctrl:1
	v_add_f32_e32 v41, v41, v43
	s_waitcnt lgkmcnt(2)
	v_mul_f32_e32 v53, v17, v53
	v_add_f32_dpp v32, v32, v32 row_half_mirror row_mask:0xf bank_mask:0xf bound_ctrl:1
	v_mul_f32_e32 v55, v19, v55
	v_fmac_f32_e32 v49, v20, v48
	v_add_f32_dpp v32, v32, v32 row_mirror row_mask:0xf bank_mask:0xf bound_ctrl:1
	v_mov_b32_e32 v42, v32
	s_nop 1
	v_permlane16_swap_b32_e32 v32, v42
	v_add_f32_e32 v32, v32, v42
	v_fmac_f32_e32 v51, v22, v50
	v_add_f32_e32 v43, v45, v47
	v_add_f32_e32 v40, 0, v41
	v_mov_b32_e32 v42, v32
	v_fmac_f32_e32 v53, v16, v52
	v_fmac_f32_e32 v55, v18, v54
	v_add_f32_e32 v45, v49, v51
	v_add_f32_e32 v40, v40, v43
	v_permlane32_swap_b32_e32 v32, v42
	v_add_f32_e32 v46, v53, v55
	v_add_f32_e32 v40, v40, v45
	v_add_f32_e32 v32, v32, v42
	v_add_f32_e32 v40, v40, v46
	v_fmamk_f32 v32, v32, 0x3a800000, v56
	s_waitcnt lgkmcnt(1)
	v_mul_f32_e32 v59, v29, v59
	v_mul_f32_e32 v61, v31, v61
	v_add_f32_dpp v40, v40, v40 quad_perm:[1,0,3,2] row_mask:0xf bank_mask:0xf bound_ctrl:1
	v_mul_f32_e32 v42, 0x4b800000, v32
	v_cmp_gt_f32_e64 s[8:9], s52, v32
	v_fmac_f32_e32 v59, v28, v58
	v_fmac_f32_e32 v61, v30, v60
	v_add_f32_dpp v40, v40, v40 quad_perm:[2,3,0,1] row_mask:0xf bank_mask:0xf bound_ctrl:1
	v_cndmask_b32_e64 v32, v32, v42, s[8:9]
	v_add_f32_e32 v47, v59, v61
	v_add_f32_dpp v40, v40, v40 row_half_mirror row_mask:0xf bank_mask:0xf bound_ctrl:1
	v_rsq_f32_e32 v32, v32
	v_add_f32_e32 v41, 0, v47
	v_add_f32_dpp v40, v40, v40 row_mirror row_mask:0xf bank_mask:0xf bound_ctrl:1
	ds_read_b128 v[44:47], v57 offset:6144
	ds_read_b128 v[48:51], v57 offset:7168
	v_mov_b32_e32 v43, v40
	s_waitcnt lgkmcnt(2)
	v_mul_f32_e32 v63, v25, v63
	v_mul_f32_e32 v65, v27, v65
	v_permlane16_swap_b32_e32 v40, v43
	v_fmac_f32_e32 v63, v24, v62
	v_add_f32_e32 v40, v40, v43
	v_mul_f32_e32 v43, 0x45800000, v32
	v_fmac_f32_e32 v65, v26, v64
	v_cndmask_b32_e64 v32, v32, v43, s[8:9]
	v_add_f32_e32 v43, v63, v65
	v_add_f32_e32 v41, v41, v43
	s_waitcnt lgkmcnt(1)
	v_mul_f32_e32 v43, v21, v45
	v_fmac_f32_e32 v43, v20, v44
	v_mul_f32_e32 v44, v23, v47
	v_fmac_f32_e32 v44, v22, v46
	v_add_f32_e32 v43, v43, v44
	v_add_f32_e32 v41, v41, v43
	s_waitcnt lgkmcnt(0)
	v_mul_f32_e32 v43, v17, v49
	v_mul_f32_e32 v44, v19, v51
	v_fmac_f32_e32 v43, v16, v48
	v_fmac_f32_e32 v44, v18, v50
	v_add_f32_e32 v43, v43, v44
	ds_read_b128 v[44:47], v57 offset:8192
	ds_read_b128 v[48:51], v57 offset:9216
	v_add_f32_e32 v41, v41, v43
	v_mov_b32_e32 v42, v40
	s_nop 1
	v_permlane32_swap_b32_e32 v40, v42
	s_waitcnt lgkmcnt(1)
	v_mul_f32_e32 v45, v29, v45
	v_fmac_f32_e32 v45, v28, v44
	v_mul_f32_e32 v44, v31, v47
	v_fmac_f32_e32 v44, v30, v46
	v_add_f32_e32 v44, v45, v44
	s_waitcnt lgkmcnt(0)
	v_mul_f32_e32 v49, v25, v49
	v_add_f32_e32 v52, 0, v44
	v_fmac_f32_e32 v49, v24, v48
	v_mul_f32_e32 v48, v27, v51
	ds_read_b128 v[44:47], v57 offset:10240
	v_fmac_f32_e32 v48, v26, v50
	v_add_f32_e32 v48, v49, v48
	v_add_f32_e32 v52, v52, v48
	ds_read_b128 v[48:51], v57 offset:11264
	s_waitcnt lgkmcnt(1)
	v_mul_f32_e32 v45, v21, v45
	v_fmac_f32_e32 v45, v20, v44
	v_mul_f32_e32 v44, v23, v47
	v_fmac_f32_e32 v44, v22, v46
	v_add_f32_e32 v44, v45, v44
	s_waitcnt lgkmcnt(0)
	v_mul_f32_e32 v45, v17, v49
	v_mul_f32_e32 v46, v19, v51
	v_fmac_f32_e32 v45, v16, v48
	v_fmac_f32_e32 v46, v18, v50
	v_add_f32_e32 v44, v52, v44
	v_add_f32_e32 v45, v45, v46
	v_add_f32_e32 v44, v44, v45
	ds_read_b128 v[48:51], v57 offset:12288
	ds_read_b128 v[52:55], v57 offset:13312
	v_add_f32_dpp v44, v44, v44 quad_perm:[1,0,3,2] row_mask:0xf bank_mask:0xf bound_ctrl:1
	v_add_f32_dpp v41, v41, v41 quad_perm:[1,0,3,2] row_mask:0xf bank_mask:0xf bound_ctrl:1
	s_waitcnt lgkmcnt(1)
	v_mul_f32_e32 v47, v31, v51
	v_add_f32_dpp v44, v44, v44 quad_perm:[2,3,0,1] row_mask:0xf bank_mask:0xf bound_ctrl:1
	v_fmac_f32_e32 v47, v30, v50
	v_add_f32_dpp v41, v41, v41 quad_perm:[2,3,0,1] row_mask:0xf bank_mask:0xf bound_ctrl:1
	v_add_f32_dpp v44, v44, v44 row_half_mirror row_mask:0xf bank_mask:0xf bound_ctrl:1
	s_nop 0
	v_add_f32_dpp v41, v41, v41 row_half_mirror row_mask:0xf bank_mask:0xf bound_ctrl:1
	v_add_f32_dpp v44, v44, v44 row_mirror row_mask:0xf bank_mask:0xf bound_ctrl:1
	v_mov_b32_e32 v45, v44
	s_nop 1
	v_permlane16_swap_b32_e32 v44, v45
	v_add_f32_e32 v44, v44, v45
	v_mul_f32_e32 v45, v29, v49
	v_fmac_f32_e32 v45, v28, v48
	ds_read_b128 v[48:51], v57 offset:14336
	v_add_f32_e32 v45, v45, v47
	s_waitcnt lgkmcnt(1)
	v_mul_f32_e32 v47, v25, v53
	v_fmac_f32_e32 v47, v24, v52
	v_mul_f32_e32 v52, v27, v55
	v_fmac_f32_e32 v52, v26, v54
	v_add_f32_e32 v45, 0, v45
	v_add_f32_e32 v47, v47, v52
	ds_read_b128 v[52:55], v57 offset:15360
	v_add_f32_e32 v45, v45, v47
	s_waitcnt lgkmcnt(1)
	v_mul_f32_e32 v47, v21, v49
	v_fmac_f32_e32 v47, v20, v48
	v_mul_f32_e32 v48, v23, v51
	v_fmac_f32_e32 v48, v22, v50
	v_add_f32_e32 v47, v47, v48
	v_add_f32_e32 v45, v45, v47
	s_waitcnt lgkmcnt(0)
	v_mul_f32_e32 v47, v17, v53
	v_mul_f32_e32 v48, v19, v55
	v_fmac_f32_e32 v47, v16, v52
	v_fmac_f32_e32 v48, v18, v54
	v_add_f32_e32 v47, v47, v48
	ds_read_b128 v[48:51], v57 offset:16384
	ds_read_b128 v[52:55], v57 offset:17408
	v_add_f32_e32 v45, v45, v47
	v_add_f32_dpp v41, v41, v41 row_mirror row_mask:0xf bank_mask:0xf bound_ctrl:1
	v_mov_b32_e32 v43, v41
	s_waitcnt lgkmcnt(1)
	v_mul_f32_e32 v49, v29, v49
	v_fmac_f32_e32 v49, v28, v48
	v_mul_f32_e32 v48, v31, v51
	v_fmac_f32_e32 v48, v30, v50
	v_add_f32_e32 v48, v49, v48
	s_waitcnt lgkmcnt(0)
	v_mul_f32_e32 v53, v25, v53
	v_add_f32_e32 v58, 0, v48
	v_fmac_f32_e32 v53, v24, v52
	v_mul_f32_e32 v52, v27, v55
	ds_read_b128 v[48:51], v57 offset:18432
	v_fmac_f32_e32 v52, v26, v54
	v_add_f32_e32 v52, v53, v52
	v_add_f32_e32 v58, v58, v52
	ds_read_b128 v[52:55], v57 offset:19456
	s_waitcnt lgkmcnt(1)
	v_mul_f32_e32 v49, v21, v49
	v_fmac_f32_e32 v49, v20, v48
	v_mul_f32_e32 v48, v23, v51
	v_fmac_f32_e32 v48, v22, v50
	v_add_f32_e32 v48, v49, v48
	s_waitcnt lgkmcnt(0)
	v_mul_f32_e32 v49, v17, v53
	v_mul_f32_e32 v50, v19, v55
	v_fmac_f32_e32 v49, v16, v52
	v_fmac_f32_e32 v50, v18, v54
	v_add_f32_e32 v48, v58, v48
	v_add_f32_e32 v49, v49, v50
	v_add_f32_e32 v48, v48, v49
	ds_read_b128 v[52:55], v57 offset:20480
	ds_read_b128 v[58:61], v57 offset:21504
	v_add_f32_dpp v48, v48, v48 quad_perm:[1,0,3,2] row_mask:0xf bank_mask:0xf bound_ctrl:1
	v_add_f32_dpp v45, v45, v45 quad_perm:[1,0,3,2] row_mask:0xf bank_mask:0xf bound_ctrl:1
	v_permlane16_swap_b32_e32 v41, v43
	v_add_f32_dpp v48, v48, v48 quad_perm:[2,3,0,1] row_mask:0xf bank_mask:0xf bound_ctrl:1
	s_waitcnt lgkmcnt(1)
	v_mul_f32_e32 v51, v31, v55
	v_fmac_f32_e32 v51, v30, v54
	v_add_f32_dpp v48, v48, v48 row_half_mirror row_mask:0xf bank_mask:0xf bound_ctrl:1
	v_add_f32_dpp v45, v45, v45 quad_perm:[2,3,0,1] row_mask:0xf bank_mask:0xf bound_ctrl:1
	v_add_f32_e32 v41, v41, v43
	v_add_f32_dpp v48, v48, v48 row_mirror row_mask:0xf bank_mask:0xf bound_ctrl:1
	v_mov_b32_e32 v49, v48
	s_nop 1
	v_permlane16_swap_b32_e32 v48, v49
	v_add_f32_e32 v48, v48, v49
	v_mul_f32_e32 v49, v29, v53
	v_fmac_f32_e32 v49, v28, v52
	ds_read_b128 v[52:55], v57 offset:22528
	v_add_f32_e32 v49, v49, v51
	s_waitcnt lgkmcnt(1)
	v_mul_f32_e32 v51, v25, v59
	v_fmac_f32_e32 v51, v24, v58
	v_mul_f32_e32 v58, v27, v61
	v_fmac_f32_e32 v58, v26, v60
	v_add_f32_e32 v49, 0, v49
	v_add_f32_e32 v51, v51, v58
	ds_read_b128 v[58:61], v57 offset:23552
	v_add_f32_e32 v49, v49, v51
	s_waitcnt lgkmcnt(1)
	v_mul_f32_e32 v51, v21, v53
	v_fmac_f32_e32 v51, v20, v52
	v_mul_f32_e32 v52, v23, v55
	v_fmac_f32_e32 v52, v22, v54
	v_add_f32_e32 v51, v51, v52
	v_add_f32_e32 v49, v49, v51
	s_waitcnt lgkmcnt(0)
	v_mul_f32_e32 v51, v17, v59
	v_mul_f32_e32 v52, v19, v61
	v_fmac_f32_e32 v51, v16, v58
	v_fmac_f32_e32 v52, v18, v60
	v_add_f32_e32 v51, v51, v52
	ds_read_b128 v[52:55], v57 offset:24576
	ds_read_b128 v[58:61], v57 offset:25600
	v_add_f32_e32 v49, v49, v51
	v_add_f32_dpp v45, v45, v45 row_half_mirror row_mask:0xf bank_mask:0xf bound_ctrl:1
	v_mov_b32_e32 v43, v41
	s_waitcnt lgkmcnt(1)
	v_mul_f32_e32 v53, v29, v53
	v_fmac_f32_e32 v53, v28, v52
	v_mul_f32_e32 v52, v31, v55
	v_fmac_f32_e32 v52, v30, v54
	v_add_f32_e32 v52, v53, v52
	s_waitcnt lgkmcnt(0)
	v_mul_f32_e32 v59, v25, v59
	v_add_f32_e32 v62, 0, v52
	v_fmac_f32_e32 v59, v24, v58
	v_mul_f32_e32 v58, v27, v61
	ds_read_b128 v[52:55], v57 offset:26624
	v_fmac_f32_e32 v58, v26, v60
	v_add_f32_e32 v58, v59, v58
	v_add_f32_e32 v62, v62, v58
	ds_read_b128 v[58:61], v57 offset:27648
	s_waitcnt lgkmcnt(1)
	v_mul_f32_e32 v53, v21, v53
	v_fmac_f32_e32 v53, v20, v52
	v_mul_f32_e32 v52, v23, v55
	v_fmac_f32_e32 v52, v22, v54
	v_add_f32_e32 v52, v53, v52
	s_waitcnt lgkmcnt(0)
	v_mul_f32_e32 v53, v17, v59
	v_mul_f32_e32 v54, v19, v61
	v_fmac_f32_e32 v53, v16, v58
	v_fmac_f32_e32 v54, v18, v60
	v_add_f32_e32 v52, v62, v52
	v_add_f32_e32 v53, v53, v54
	v_add_f32_e32 v52, v52, v53
	ds_read_b128 v[58:61], v57 offset:28672
	ds_read_b128 v[62:65], v57 offset:29696
	v_add_f32_dpp v52, v52, v52 quad_perm:[1,0,3,2] row_mask:0xf bank_mask:0xf bound_ctrl:1
	v_add_f32_dpp v49, v49, v49 quad_perm:[1,0,3,2] row_mask:0xf bank_mask:0xf bound_ctrl:1
	v_add_f32_dpp v45, v45, v45 row_mirror row_mask:0xf bank_mask:0xf bound_ctrl:1
	v_add_f32_dpp v52, v52, v52 quad_perm:[2,3,0,1] row_mask:0xf bank_mask:0xf bound_ctrl:1
	s_waitcnt lgkmcnt(1)
	v_mul_f32_e32 v55, v31, v61
	v_fmac_f32_e32 v55, v30, v60
	v_add_f32_dpp v52, v52, v52 row_half_mirror row_mask:0xf bank_mask:0xf bound_ctrl:1
	v_add_f32_dpp v49, v49, v49 quad_perm:[2,3,0,1] row_mask:0xf bank_mask:0xf bound_ctrl:1
	v_mov_b32_e32 v47, v45
	v_add_f32_dpp v52, v52, v52 row_mirror row_mask:0xf bank_mask:0xf bound_ctrl:1
	v_mov_b32_e32 v53, v52
	s_nop 1
	v_permlane16_swap_b32_e32 v52, v53
	v_add_f32_e32 v52, v52, v53
	v_mul_f32_e32 v53, v29, v59
	v_fmac_f32_e32 v53, v28, v58
	ds_read_b128 v[58:61], v57 offset:30720
	v_add_f32_e32 v53, v53, v55
	s_waitcnt lgkmcnt(1)
	v_mul_f32_e32 v55, v25, v63
	v_fmac_f32_e32 v55, v24, v62
	v_mul_f32_e32 v62, v27, v65
	v_fmac_f32_e32 v62, v26, v64
	v_add_f32_e32 v53, 0, v53
	v_add_f32_e32 v55, v55, v62
	ds_read_b128 v[62:65], v57 offset:31744
	v_add_f32_e32 v53, v53, v55
	s_waitcnt lgkmcnt(1)
	v_mul_f32_e32 v55, v21, v59
	v_fmac_f32_e32 v55, v20, v58
	v_mul_f32_e32 v58, v23, v61
	v_fmac_f32_e32 v58, v22, v60
	v_add_f32_e32 v55, v55, v58
	v_add_f32_e32 v53, v53, v55
	s_waitcnt lgkmcnt(0)
	v_mul_f32_e32 v55, v17, v63
	v_mul_f32_e32 v58, v19, v65
	v_fmac_f32_e32 v55, v16, v62
	v_fmac_f32_e32 v58, v18, v64
	v_add_f32_e32 v55, v55, v58
	v_add_f32_e32 v53, v53, v55
	v_add_f32_dpp v49, v49, v49 row_half_mirror row_mask:0xf bank_mask:0xf bound_ctrl:1
	v_permlane16_swap_b32_e32 v45, v47
	v_add_f32_dpp v53, v53, v53 quad_perm:[1,0,3,2] row_mask:0xf bank_mask:0xf bound_ctrl:1
	v_add_f32_dpp v49, v49, v49 row_mirror row_mask:0xf bank_mask:0xf bound_ctrl:1
	v_mov_b32_e32 v51, v49
	v_add_f32_dpp v53, v53, v53 quad_perm:[2,3,0,1] row_mask:0xf bank_mask:0xf bound_ctrl:1
	s_nop 0
	v_permlane16_swap_b32_e32 v49, v51
	v_add_f32_dpp v53, v53, v53 row_half_mirror row_mask:0xf bank_mask:0xf bound_ctrl:1
	v_add_f32_e32 v45, v45, v47
	v_add_f32_e32 v49, v49, v51
	v_add_f32_dpp v53, v53, v53 row_mirror row_mask:0xf bank_mask:0xf bound_ctrl:1
	v_mov_b32_e32 v55, v53
	s_nop 1
	v_permlane16_swap_b32_e32 v53, v55
	v_add_f32_e32 v53, v53, v55
	v_mov_b32_e32 v46, v44
	v_mov_b32_e32 v47, v45
	v_mov_b32_e32 v50, v48
	v_mov_b32_e32 v51, v49
	v_mov_b32_e32 v54, v52
	v_mov_b32_e32 v55, v53
	v_permlane32_swap_b32_e32 v41, v43
	v_permlane32_swap_b32_e32 v44, v46
	v_permlane32_swap_b32_e32 v45, v47
	v_permlane32_swap_b32_e32 v48, v50
	v_permlane32_swap_b32_e32 v49, v51
	v_permlane32_swap_b32_e32 v52, v54
	v_permlane32_swap_b32_e32 v53, v55
	s_and_saveexec_b64 s[8:9], vcc
	s_cbranch_execz .LBB0_39
	s_lshl_b64 s[16:17], s[46:47], 5
	v_pk_add_f32 v[40:41], v[40:41], v[42:43]
	v_pk_add_f32 v[42:43], v[44:45], v[46:47]
	s_add_u32 s16, s4, s16
	v_pk_mul_f32 v[42:43], v[32:33], v[42:43] op_sel_hi:[0,1]
	v_pk_mul_f32 v[40:41], v[32:33], v[40:41] op_sel_hi:[0,1]
	v_pk_add_f32 v[44:45], v[48:49], v[50:51]
	v_pk_add_f32 v[46:47], v[52:53], v[54:55]
	s_addc_u32 s17, s5, s17
	v_pk_mul_f32 v[46:47], v[32:33], v[46:47] op_sel_hi:[0,1]
	v_pk_mul_f32 v[44:45], v[32:33], v[44:45] op_sel_hi:[0,1]
	global_store_dwordx4 v33, v[40:43], s[16:17] sc1
	global_store_dwordx4 v33, v[44:47], s[16:17] offset:16 sc1
.LBB0_39:
	s_or_b64 exec, exec, s[8:9]
	s_lshl_b64 s[8:9], s[46:47], 11
	v_mul_f32_e32 v28, v28, v32
	v_mul_f32_e32 v29, v29, v32
	v_mul_f32_e32 v30, v30, v32
	v_mul_f32_e32 v31, v31, v32
	v_lshl_add_u64 v[44:45], v[38:39], 0, s[8:9]
	v_mul_f32_e32 v24, v24, v32
	v_mul_f32_e32 v25, v25, v32
	v_mul_f32_e32 v26, v26, v32
	v_mul_f32_e32 v27, v27, v32
	v_mul_f32_e32 v20, v20, v32
	v_mul_f32_e32 v21, v21, v32
	v_mul_f32_e32 v22, v22, v32
	v_mul_f32_e32 v23, v23, v32
	v_mul_f32_e32 v16, v16, v32
	v_mul_f32_e32 v17, v17, v32
	v_mul_f32_e32 v18, v18, v32
	v_mul_f32_e32 v19, v19, v32
	s_cmpk_gt_i32 s14, 0x3fff
	v_mul_f32_e32 v28, v28, v76
	v_mul_f32_e32 v29, v29, v77
	v_mul_f32_e32 v30, v30, v78
	v_mul_f32_e32 v31, v31, v79
	v_cvt_pk_bf16_f32 v28, v28, v29
	v_cvt_pk_bf16_f32 v29, v30, v31
	global_store_dwordx2 v[44:45], v[28:29], off sc1
	v_mul_f32_e32 v24, v24, v80
	v_mul_f32_e32 v25, v25, v81
	v_mul_f32_e32 v26, v26, v82
	v_mul_f32_e32 v27, v27, v83
	v_cvt_pk_bf16_f32 v24, v24, v25
	v_cvt_pk_bf16_f32 v25, v26, v27
	global_store_dwordx2 v[44:45], v[24:25], off offset:512 sc1
	v_mul_f32_e32 v20, v20, v84
	v_mul_f32_e32 v21, v21, v85
	v_mul_f32_e32 v22, v22, v86
	v_mul_f32_e32 v23, v23, v87
	v_cvt_pk_bf16_f32 v20, v20, v21
	v_cvt_pk_bf16_f32 v21, v22, v23
	global_store_dwordx2 v[44:45], v[20:21], off offset:1024 sc1
	v_mul_f32_e32 v16, v16, v88
	v_mul_f32_e32 v17, v17, v89
	v_mul_f32_e32 v18, v18, v90
	v_mul_f32_e32 v19, v19, v91
	v_cvt_pk_bf16_f32 v16, v16, v17
	v_cvt_pk_bf16_f32 v17, v18, v19
	global_store_dwordx2 v[44:45], v[16:17], off offset:1536 sc1
	s_cbranch_scc1 .LBB0_36
	v_mul_f32_e32 v16, v13, v13
	v_mul_f32_e32 v17, v15, v15
	v_fmac_f32_e32 v16, v12, v12
	v_fmac_f32_e32 v17, v14, v14
	v_add_f32_e32 v16, v16, v17
	v_mul_f32_e32 v17, v9, v9
	v_mul_f32_e32 v18, v11, v11
	v_fmac_f32_e32 v17, v8, v8
	v_fmac_f32_e32 v18, v10, v10
	v_add_f32_e32 v17, v17, v18
	v_add_f32_e32 v16, v16, v17
	v_mul_f32_e32 v17, v5, v5
	v_mul_f32_e32 v18, v7, v7
	v_fmac_f32_e32 v17, v4, v4
	v_fmac_f32_e32 v18, v6, v6
	v_add_f32_e32 v17, v17, v18
	v_add_f32_e32 v16, v16, v17
	v_mul_f32_e32 v17, v1, v1
	v_mul_f32_e32 v18, v3, v3
	v_fmac_f32_e32 v17, v0, v0
	v_fmac_f32_e32 v18, v2, v2
	v_add_f32_e32 v17, v17, v18
	v_add_f32_e32 v16, v16, v17
	s_nop 1
	v_add_f32_dpp v16, v16, v16 quad_perm:[1,0,3,2] row_mask:0xf bank_mask:0xf bound_ctrl:1
	s_nop 1
	v_add_f32_dpp v16, v16, v16 quad_perm:[2,3,0,1] row_mask:0xf bank_mask:0xf bound_ctrl:1
	s_nop 1
	v_add_f32_dpp v16, v16, v16 row_half_mirror row_mask:0xf bank_mask:0xf bound_ctrl:1
	s_nop 1
	v_add_f32_dpp v16, v16, v16 row_mirror row_mask:0xf bank_mask:0xf bound_ctrl:1
	v_mov_b32_e32 v17, v16
	s_nop 1
	v_permlane16_swap_b32_e32 v16, v17
	v_add_f32_e32 v20, v16, v17
	v_mov_b32_e32 v21, v20
	ds_read_b128 v[16:19], v57
	s_nop 0
	v_permlane32_swap_b32_e32 v20, v21
	v_add_f32_e32 v20, v20, v21
	v_fmamk_f32 v32, v20, 0x3a800000, v56
	ds_read_b128 v[20:23], v57 offset:1024
	s_waitcnt lgkmcnt(1)
	v_mul_f32_e32 v17, v13, v17
	v_fmac_f32_e32 v17, v12, v16
	v_mul_f32_e32 v16, v15, v19
	v_fmac_f32_e32 v16, v14, v18
	v_add_f32_e32 v16, v17, v16
	s_waitcnt lgkmcnt(0)
	v_mul_f32_e32 v21, v9, v21
	v_add_f32_e32 v24, 0, v16
	v_fmac_f32_e32 v21, v8, v20
	v_mul_f32_e32 v20, v11, v23
	ds_read_b128 v[16:19], v57 offset:2048
	v_fmac_f32_e32 v20, v10, v22
	v_add_f32_e32 v20, v21, v20
	v_add_f32_e32 v24, v24, v20
	ds_read_b128 v[20:23], v57 offset:3072
	s_waitcnt lgkmcnt(1)
	v_mul_f32_e32 v17, v5, v17
	v_fmac_f32_e32 v17, v4, v16
	v_mul_f32_e32 v16, v7, v19
	v_fmac_f32_e32 v16, v6, v18
	v_add_f32_e32 v16, v17, v16
	s_waitcnt lgkmcnt(0)
	v_mul_f32_e32 v17, v1, v21
	v_mul_f32_e32 v18, v3, v23
	v_fmac_f32_e32 v17, v0, v20
	v_fmac_f32_e32 v18, v2, v22
	v_add_f32_e32 v16, v24, v16
	v_add_f32_e32 v17, v17, v18
	v_add_f32_e32 v16, v16, v17
	ds_read_b128 v[20:23], v57 offset:4096
	ds_read_b128 v[24:27], v57 offset:5120
	v_add_f32_dpp v16, v16, v16 quad_perm:[1,0,3,2] row_mask:0xf bank_mask:0xf bound_ctrl:1
	v_cmp_gt_f32_e64 s[8:9], s52, v32
	s_waitcnt lgkmcnt(1)
	v_mul_f32_e32 v19, v15, v23
	v_add_f32_dpp v16, v16, v16 quad_perm:[2,3,0,1] row_mask:0xf bank_mask:0xf bound_ctrl:1
	v_fmac_f32_e32 v19, v14, v22
	s_nop 0
	v_add_f32_dpp v16, v16, v16 row_half_mirror row_mask:0xf bank_mask:0xf bound_ctrl:1
	s_nop 1
	v_add_f32_dpp v16, v16, v16 row_mirror row_mask:0xf bank_mask:0xf bound_ctrl:1
	v_mov_b32_e32 v17, v16
	s_nop 1
	v_permlane16_swap_b32_e32 v16, v17
	v_add_f32_e32 v16, v16, v17
	v_mul_f32_e32 v17, v13, v21
	v_fmac_f32_e32 v17, v12, v20
	ds_read_b128 v[20:23], v57 offset:6144
	v_add_f32_e32 v17, v17, v19
	s_waitcnt lgkmcnt(1)
	v_mul_f32_e32 v19, v9, v25
	v_fmac_f32_e32 v19, v8, v24
	v_mul_f32_e32 v24, v11, v27
	v_fmac_f32_e32 v24, v10, v26
	v_add_f32_e32 v17, 0, v17
	v_add_f32_e32 v19, v19, v24
	ds_read_b128 v[24:27], v57 offset:7168
	v_add_f32_e32 v17, v17, v19
	s_waitcnt lgkmcnt(1)
	v_mul_f32_e32 v19, v5, v21
	v_fmac_f32_e32 v19, v4, v20
	v_mul_f32_e32 v20, v7, v23
	v_fmac_f32_e32 v20, v6, v22
	v_add_f32_e32 v19, v19, v20
	v_add_f32_e32 v17, v17, v19
	s_waitcnt lgkmcnt(0)
	v_mul_f32_e32 v19, v1, v25
	v_mul_f32_e32 v20, v3, v27
	v_fmac_f32_e32 v19, v0, v24
	v_fmac_f32_e32 v20, v2, v26
	v_add_f32_e32 v19, v19, v20
	ds_read_b128 v[20:23], v57 offset:8192
	ds_read_b128 v[24:27], v57 offset:9216
	v_add_f32_e32 v17, v17, v19
	v_mov_b32_e32 v18, v16
	s_nop 1
	v_permlane32_swap_b32_e32 v16, v18
	s_waitcnt lgkmcnt(1)
	v_mul_f32_e32 v21, v13, v21
	v_fmac_f32_e32 v21, v12, v20
	v_mul_f32_e32 v20, v15, v23
	v_fmac_f32_e32 v20, v14, v22
	v_add_f32_e32 v20, v21, v20
	s_waitcnt lgkmcnt(0)
	v_mul_f32_e32 v25, v9, v25
	v_add_f32_e32 v28, 0, v20
	v_fmac_f32_e32 v25, v8, v24
	v_mul_f32_e32 v24, v11, v27
	ds_read_b128 v[20:23], v57 offset:10240
	v_fmac_f32_e32 v24, v10, v26
	v_add_f32_e32 v24, v25, v24
	v_add_f32_e32 v28, v28, v24
	ds_read_b128 v[24:27], v57 offset:11264
	s_waitcnt lgkmcnt(1)
	v_mul_f32_e32 v21, v5, v21
	v_fmac_f32_e32 v21, v4, v20
	v_mul_f32_e32 v20, v7, v23
	v_fmac_f32_e32 v20, v6, v22
	v_add_f32_e32 v20, v21, v20
	s_waitcnt lgkmcnt(0)
	v_mul_f32_e32 v21, v1, v25
	v_mul_f32_e32 v22, v3, v27
	v_fmac_f32_e32 v21, v0, v24
	v_fmac_f32_e32 v22, v2, v26
	v_add_f32_e32 v20, v28, v20
	v_add_f32_e32 v21, v21, v22
	v_add_f32_e32 v20, v20, v21
	ds_read_b128 v[24:27], v57 offset:12288
	ds_read_b128 v[28:31], v57 offset:13312
	v_add_f32_dpp v20, v20, v20 quad_perm:[1,0,3,2] row_mask:0xf bank_mask:0xf bound_ctrl:1
	v_add_f32_dpp v17, v17, v17 quad_perm:[1,0,3,2] row_mask:0xf bank_mask:0xf bound_ctrl:1
	s_waitcnt lgkmcnt(1)
	v_mul_f32_e32 v23, v15, v27
	v_add_f32_dpp v20, v20, v20 quad_perm:[2,3,0,1] row_mask:0xf bank_mask:0xf bound_ctrl:1
	v_fmac_f32_e32 v23, v14, v26
	v_add_f32_dpp v17, v17, v17 quad_perm:[2,3,0,1] row_mask:0xf bank_mask:0xf bound_ctrl:1
	v_add_f32_dpp v20, v20, v20 row_half_mirror row_mask:0xf bank_mask:0xf bound_ctrl:1
	s_nop 0
	v_add_f32_dpp v17, v17, v17 row_half_mirror row_mask:0xf bank_mask:0xf bound_ctrl:1
	v_add_f32_dpp v20, v20, v20 row_mirror row_mask:0xf bank_mask:0xf bound_ctrl:1
	v_mov_b32_e32 v21, v20
	s_nop 1
	v_permlane16_swap_b32_e32 v20, v21
	v_add_f32_e32 v20, v20, v21
	v_mul_f32_e32 v21, v13, v25
	v_fmac_f32_e32 v21, v12, v24
	ds_read_b128 v[24:27], v57 offset:14336
	v_add_f32_e32 v21, v21, v23
	s_waitcnt lgkmcnt(1)
	v_mul_f32_e32 v23, v9, v29
	v_fmac_f32_e32 v23, v8, v28
	v_mul_f32_e32 v28, v11, v31
	v_fmac_f32_e32 v28, v10, v30
	v_add_f32_e32 v21, 0, v21
	v_add_f32_e32 v23, v23, v28
	ds_read_b128 v[28:31], v57 offset:15360
	v_add_f32_e32 v21, v21, v23
	s_waitcnt lgkmcnt(1)
	v_mul_f32_e32 v23, v5, v25
	v_fmac_f32_e32 v23, v4, v24
	v_mul_f32_e32 v24, v7, v27
	v_fmac_f32_e32 v24, v6, v26
	v_add_f32_e32 v23, v23, v24
	v_add_f32_e32 v21, v21, v23
	s_waitcnt lgkmcnt(0)
	v_mul_f32_e32 v23, v1, v29
	v_mul_f32_e32 v24, v3, v31
	v_fmac_f32_e32 v23, v0, v28
	v_fmac_f32_e32 v24, v2, v30
	v_add_f32_e32 v23, v23, v24
	ds_read_b128 v[24:27], v57 offset:16384
	ds_read_b128 v[28:31], v57 offset:17408
	v_add_f32_e32 v21, v21, v23
	v_add_f32_dpp v17, v17, v17 row_mirror row_mask:0xf bank_mask:0xf bound_ctrl:1
	v_mov_b32_e32 v19, v17
	s_waitcnt lgkmcnt(1)
	v_mul_f32_e32 v25, v13, v25
	v_fmac_f32_e32 v25, v12, v24
	v_mul_f32_e32 v24, v15, v27
	v_fmac_f32_e32 v24, v14, v26
	v_add_f32_e32 v24, v25, v24
	s_waitcnt lgkmcnt(0)
	v_mul_f32_e32 v29, v9, v29
	v_add_f32_e32 v40, 0, v24
	v_fmac_f32_e32 v29, v8, v28
	v_mul_f32_e32 v28, v11, v31
	ds_read_b128 v[24:27], v57 offset:18432
	v_fmac_f32_e32 v28, v10, v30
	v_add_f32_e32 v28, v29, v28
	v_add_f32_e32 v40, v40, v28
	ds_read_b128 v[28:31], v57 offset:19456
	s_waitcnt lgkmcnt(1)
	v_mul_f32_e32 v25, v5, v25
	v_fmac_f32_e32 v25, v4, v24
	v_mul_f32_e32 v24, v7, v27
	v_fmac_f32_e32 v24, v6, v26
	v_add_f32_e32 v24, v25, v24
	s_waitcnt lgkmcnt(0)
	v_mul_f32_e32 v25, v1, v29
	v_mul_f32_e32 v26, v3, v31
	v_fmac_f32_e32 v25, v0, v28
	v_fmac_f32_e32 v26, v2, v30
	v_add_f32_e32 v24, v40, v24
	v_add_f32_e32 v25, v25, v26
	v_add_f32_e32 v24, v24, v25
	ds_read_b128 v[28:31], v57 offset:20480
	ds_read_b128 v[40:43], v57 offset:21504
	v_add_f32_dpp v24, v24, v24 quad_perm:[1,0,3,2] row_mask:0xf bank_mask:0xf bound_ctrl:1
	v_add_f32_dpp v21, v21, v21 quad_perm:[1,0,3,2] row_mask:0xf bank_mask:0xf bound_ctrl:1
	v_permlane16_swap_b32_e32 v17, v19
	v_add_f32_dpp v24, v24, v24 quad_perm:[2,3,0,1] row_mask:0xf bank_mask:0xf bound_ctrl:1
	s_waitcnt lgkmcnt(1)
	v_mul_f32_e32 v27, v15, v31
	v_fmac_f32_e32 v27, v14, v30
	v_add_f32_dpp v24, v24, v24 row_half_mirror row_mask:0xf bank_mask:0xf bound_ctrl:1
	v_add_f32_dpp v21, v21, v21 quad_perm:[2,3,0,1] row_mask:0xf bank_mask:0xf bound_ctrl:1
	v_add_f32_e32 v17, v17, v19
	v_add_f32_dpp v24, v24, v24 row_mirror row_mask:0xf bank_mask:0xf bound_ctrl:1
	v_mov_b32_e32 v25, v24
	s_nop 1
	v_permlane16_swap_b32_e32 v24, v25
	v_add_f32_e32 v24, v24, v25
	v_mul_f32_e32 v25, v13, v29
	v_fmac_f32_e32 v25, v12, v28
	ds_read_b128 v[28:31], v57 offset:22528
	v_add_f32_e32 v25, v25, v27
	s_waitcnt lgkmcnt(1)
	v_mul_f32_e32 v27, v9, v41
	v_fmac_f32_e32 v27, v8, v40
	v_mul_f32_e32 v40, v11, v43
	v_fmac_f32_e32 v40, v10, v42
	v_add_f32_e32 v25, 0, v25
	v_add_f32_e32 v27, v27, v40
	ds_read_b128 v[40:43], v57 offset:23552
	v_add_f32_e32 v25, v25, v27
	s_waitcnt lgkmcnt(1)
	v_mul_f32_e32 v27, v5, v29
	v_fmac_f32_e32 v27, v4, v28
	v_mul_f32_e32 v28, v7, v31
	v_fmac_f32_e32 v28, v6, v30
	v_add_f32_e32 v27, v27, v28
	v_add_f32_e32 v25, v25, v27
	s_waitcnt lgkmcnt(0)
	v_mul_f32_e32 v27, v1, v41
	v_mul_f32_e32 v28, v3, v43
	v_fmac_f32_e32 v27, v0, v40
	v_fmac_f32_e32 v28, v2, v42
	v_add_f32_e32 v27, v27, v28
	ds_read_b128 v[28:31], v57 offset:24576
	ds_read_b128 v[40:43], v57 offset:25600
	v_add_f32_e32 v25, v25, v27
	v_add_f32_dpp v21, v21, v21 row_half_mirror row_mask:0xf bank_mask:0xf bound_ctrl:1
	v_mov_b32_e32 v19, v17
	s_waitcnt lgkmcnt(1)
	v_mul_f32_e32 v29, v13, v29
	v_fmac_f32_e32 v29, v12, v28
	v_mul_f32_e32 v28, v15, v31
	v_fmac_f32_e32 v28, v14, v30
	v_add_f32_e32 v28, v29, v28
	s_waitcnt lgkmcnt(0)
	v_mul_f32_e32 v41, v9, v41
	v_add_f32_e32 v44, 0, v28
	v_fmac_f32_e32 v41, v8, v40
	v_mul_f32_e32 v40, v11, v43
	ds_read_b128 v[28:31], v57 offset:26624
	v_fmac_f32_e32 v40, v10, v42
	v_add_f32_e32 v40, v41, v40
	v_add_f32_e32 v44, v44, v40
	ds_read_b128 v[40:43], v57 offset:27648
	s_waitcnt lgkmcnt(1)
	v_mul_f32_e32 v29, v5, v29
	v_fmac_f32_e32 v29, v4, v28
	v_mul_f32_e32 v28, v7, v31
	v_fmac_f32_e32 v28, v6, v30
	v_add_f32_e32 v28, v29, v28
	s_waitcnt lgkmcnt(0)
	v_mul_f32_e32 v29, v1, v41
	v_mul_f32_e32 v30, v3, v43
	v_fmac_f32_e32 v29, v0, v40
	v_fmac_f32_e32 v30, v2, v42
	v_add_f32_e32 v28, v44, v28
	v_add_f32_e32 v29, v29, v30
	v_add_f32_e32 v28, v28, v29
	ds_read_b128 v[40:43], v57 offset:28672
	ds_read_b128 v[44:47], v57 offset:29696
	v_add_f32_dpp v28, v28, v28 quad_perm:[1,0,3,2] row_mask:0xf bank_mask:0xf bound_ctrl:1
	v_add_f32_dpp v25, v25, v25 quad_perm:[1,0,3,2] row_mask:0xf bank_mask:0xf bound_ctrl:1
	v_add_f32_dpp v21, v21, v21 row_mirror row_mask:0xf bank_mask:0xf bound_ctrl:1
	v_add_f32_dpp v28, v28, v28 quad_perm:[2,3,0,1] row_mask:0xf bank_mask:0xf bound_ctrl:1
	s_waitcnt lgkmcnt(1)
	v_mul_f32_e32 v31, v15, v43
	v_fmac_f32_e32 v31, v14, v42
	v_add_f32_dpp v28, v28, v28 row_half_mirror row_mask:0xf bank_mask:0xf bound_ctrl:1
	v_add_f32_dpp v25, v25, v25 quad_perm:[2,3,0,1] row_mask:0xf bank_mask:0xf bound_ctrl:1
	v_mov_b32_e32 v23, v21
	v_add_f32_dpp v28, v28, v28 row_mirror row_mask:0xf bank_mask:0xf bound_ctrl:1
	v_mov_b32_e32 v29, v28
	s_nop 1
	v_permlane16_swap_b32_e32 v28, v29
	v_add_f32_e32 v28, v28, v29
	v_mul_f32_e32 v29, v13, v41
	v_fmac_f32_e32 v29, v12, v40
	ds_read_b128 v[40:43], v57 offset:30720
	v_add_f32_e32 v29, v29, v31
	s_waitcnt lgkmcnt(1)
	v_mul_f32_e32 v31, v9, v45
	v_fmac_f32_e32 v31, v8, v44
	v_mul_f32_e32 v44, v11, v47
	v_fmac_f32_e32 v44, v10, v46
	v_add_f32_e32 v29, 0, v29
	v_add_f32_e32 v31, v31, v44
	ds_read_b128 v[44:47], v57 offset:31744
	v_add_f32_e32 v29, v29, v31
	s_waitcnt lgkmcnt(1)
	v_mul_f32_e32 v31, v5, v41
	v_fmac_f32_e32 v31, v4, v40
	v_mul_f32_e32 v40, v7, v43
	v_fmac_f32_e32 v40, v6, v42
	v_add_f32_e32 v31, v31, v40
	v_add_f32_e32 v29, v29, v31
	s_waitcnt lgkmcnt(0)
	v_mul_f32_e32 v31, v1, v45
	v_mul_f32_e32 v40, v3, v47
	v_fmac_f32_e32 v31, v0, v44
	v_fmac_f32_e32 v40, v2, v46
	v_add_f32_e32 v31, v31, v40
	v_add_f32_e32 v29, v29, v31
	v_add_f32_dpp v25, v25, v25 row_half_mirror row_mask:0xf bank_mask:0xf bound_ctrl:1
	v_permlane16_swap_b32_e32 v21, v23
	v_add_f32_dpp v29, v29, v29 quad_perm:[1,0,3,2] row_mask:0xf bank_mask:0xf bound_ctrl:1
	v_add_f32_dpp v25, v25, v25 row_mirror row_mask:0xf bank_mask:0xf bound_ctrl:1
	v_mov_b32_e32 v27, v25
	v_add_f32_dpp v29, v29, v29 quad_perm:[2,3,0,1] row_mask:0xf bank_mask:0xf bound_ctrl:1
	s_nop 0
	v_permlane16_swap_b32_e32 v25, v27
	v_add_f32_dpp v29, v29, v29 row_half_mirror row_mask:0xf bank_mask:0xf bound_ctrl:1
	v_add_f32_e32 v21, v21, v23
	v_add_f32_e32 v25, v25, v27
	v_add_f32_dpp v29, v29, v29 row_mirror row_mask:0xf bank_mask:0xf bound_ctrl:1
	v_mov_b32_e32 v31, v29
	s_nop 1
	v_permlane16_swap_b32_e32 v29, v31
	v_add_f32_e32 v29, v29, v31
	v_mov_b32_e32 v22, v20
	v_mov_b32_e32 v23, v21
	v_mov_b32_e32 v26, v24
	v_mov_b32_e32 v27, v25
	v_mov_b32_e32 v30, v28
	v_mov_b32_e32 v31, v29
	v_permlane32_swap_b32_e32 v17, v19
	v_permlane32_swap_b32_e32 v20, v22
	v_permlane32_swap_b32_e32 v21, v23
	v_permlane32_swap_b32_e32 v24, v26
	v_permlane32_swap_b32_e32 v25, v27
	v_permlane32_swap_b32_e32 v28, v30
	v_permlane32_swap_b32_e32 v29, v31
	s_and_saveexec_b64 s[16:17], s[6:7]
	s_xor_b64 s[16:17], exec, s[16:17]
	s_ashr_i32 s15, s14, 31
	s_or_saveexec_b64 s[16:17], s[16:17]
	v_mul_f32_e32 v40, 0x4b800000, v32
	v_cndmask_b32_e64 v32, v32, v40, s[8:9]
	v_rsq_f32_e32 v32, v32
	s_nop 0
	v_mul_f32_e32 v40, 0x45800000, v32
	v_cndmask_b32_e64 v32, v32, v40, s[8:9]
	v_mov_b64_e32 v[40:41], s[14:15]
	s_xor_b64 exec, exec, s[16:17]
	s_cbranch_execz .LBB0_35
	s_ashr_i32 s15, s14, 31
	s_lshl_b64 s[8:9], s[14:15], 5
	v_pk_add_f32 v[16:17], v[16:17], v[18:19]
	v_pk_add_f32 v[18:19], v[20:21], v[22:23]
	s_add_u32 s8, s4, s8
	v_pk_mul_f32 v[18:19], v[32:33], v[18:19] op_sel_hi:[0,1]
	v_pk_mul_f32 v[16:17], v[32:33], v[16:17] op_sel_hi:[0,1]
	v_pk_add_f32 v[20:21], v[24:25], v[26:27]
	v_pk_add_f32 v[22:23], v[28:29], v[30:31]
	s_addc_u32 s9, s5, s9
	v_mov_b64_e32 v[40:41], s[14:15]
	v_pk_mul_f32 v[22:23], v[32:33], v[22:23] op_sel_hi:[0,1]
	v_pk_mul_f32 v[20:21], v[32:33], v[20:21] op_sel_hi:[0,1]
	global_store_dwordx4 v33, v[16:19], s[8:9] sc1
	global_store_dwordx4 v33, v[20:23], s[8:9] offset:16 sc1
	s_branch .LBB0_35
